# speedup vs baseline: 1.0040x; 1.0025x over previous
; #define LAS __attribute__((address_space(3)))
; template <int S> __device__ __forceinline__ void fsm_chunk(f32x16& c0, f32x16& c1, float& ps, bf16x8& pa0, bf16x8& pa1, bf16x8& pa2, bf16x8& pa3) {
;   if constexpr (S < 8) { c1[2 * S] = __builtin_amdgcn_exp2f(c1[2 * S]); c1[2 * S + 1] = __builtin_amdgcn_exp2f(c1[2 * S + 1]); ps += c0[2 * S]; ps += c0[2 * S + 1]; if constexpr (S > 0) { ps += c1[2 * S - 2]; ps += c1[2 * S - 1]; } asm volatile("" : "+v"(c1), "+v"(ps)); }
;   else if constexpr (S == 8) { ps += c1[14]; ps += c1[15]; PK4(c0, 0, pa0); asm volatile("" : "+v"(pa0), "+v"(ps)); }
;   else if constexpr (S == 9) { PK4(c0, 8, pa1); asm volatile("" : "+v"(pa1)); }
;   else if constexpr (S == 10) { PK4(c1, 0, pa2); asm volatile("" : "+v"(pa2)); }
;   else { PK4(c1, 8, pa3); asm volatile("" : "+v"(pa3)); }
; }
; __device__ __forceinline__ void qk_fsm(f32x16& n0, f32x16& n1, f32x16& c0, f32x16& c1, float alC, float& l_reg, bf16x8& pa0, bf16x8& pa1, bf16x8& pa2, bf16x8& pa3,
;                                        const LAS char* kl, const int (&kx)[4], const bf16x8* qr, const LAS char* qrl) {
;   float ps = 0.f;
;     ...
;   QSLOT(0) QSLOT(1) QSLOT(2) QSLOT(3) QSLOT(4) QSLOT(5) QSLOT(6) QSLOT(7) QSLOT(8) QSLOT(9) QSLOT(10) QSLOT(11)
;     ...
;   { auto rr = __builtin_amdgcn_permlane32_swap(__float_as_uint(ps), __float_as_uint(ps), false, false); ps = __uint_as_float(rr[0]) + __uint_as_float(rr[1]); }
;   l_reg = l_reg * alC + ps;
; }
.LBB0_1011:
	ds_read_b128 v[230:233], v186 offset:57344
	ds_read_b128 v[234:237], v187 offset:12288
	s_add_u32 s4, s12, s31
	s_addc_u32 s5, s13, s9
	s_add_u32 s4, s4, 0x1dd0c000
	s_addc_u32 s5, s5, 0
	s_add_u32 s6, s12, s90
	s_addc_u32 s7, s13, s91
	s_add_u32 s6, s6, 0x25504000
	s_addc_u32 s7, s7, 0
	s_waitcnt lgkmcnt(0)
	ds_read_b128 v[244:247], v186 offset:57600
	ds_read_b128 v[248:251], v187 offset:12544
	ds_read_b128 v[238:241], v215
	v_exp_f32_e32 v64, v64
	v_exp_f32_e32 v65, v65
	v_mfma_f32_32x32x16_bf16 v[112:127], v[230:233], v[128:131], 0
	v_add_f32_e32 v96, 0, v80
	v_add_f32_e32 v162, v81, v96
	s_add_i32 m0, s98, 0x8000
	v_mfma_f32_32x32x16_bf16 v[96:111], v[234:237], v[128:131], 0
	global_load_lds_dwordx4 v177, s[4:5]
	s_waitcnt lgkmcnt(0)
	ds_read_b128 v[230:233], v188 offset:57344
	ds_read_b128 v[234:237], v189 offset:12288
	v_add_f32_e32 v162, v82, v162
	v_add_f32_e32 v162, v83, v162
	v_add_f32_e32 v162, v64, v162
	v_mfma_f32_32x32x16_bf16 v[112:127], v[244:247], v[238:241], v[112:127]
	v_exp_f32_e32 v66, v66
	v_exp_f32_e32 v67, v67
	v_add_f32_e32 v162, v65, v162
	s_add_i32 m0, s98, 0xa000
	v_mfma_f32_32x32x16_bf16 v[96:111], v[248:251], v[238:241], v[96:111]
	global_load_lds_dwordx4 v178, s[4:5]
	s_waitcnt lgkmcnt(0)
	ds_read_b128 v[244:247], v188 offset:57600
	ds_read_b128 v[248:251], v189 offset:12544
	ds_read_b128 v[238:241], v215 offset:1024
	v_add_f32_e32 v162, v84, v162
	v_add_f32_e32 v162, v85, v162
	v_add_f32_e32 v162, v66, v162
	v_mfma_f32_32x32x16_bf16 v[112:127], v[230:233], v[132:135], v[112:127]
	v_exp_f32_e32 v68, v68
	v_exp_f32_e32 v69, v69
	v_add_f32_e32 v162, v67, v162
	s_add_i32 m0, s98, 0xc000
	v_mfma_f32_32x32x16_bf16 v[96:111], v[234:237], v[132:135], v[96:111]
	global_load_lds_dwordx4 v179, s[4:5]
	s_waitcnt lgkmcnt(0)
	ds_read_b128 v[230:233], v190 offset:57344
	ds_read_b128 v[234:237], v191 offset:12288
	v_add_f32_e32 v162, v86, v162
	v_add_f32_e32 v162, v87, v162
	v_add_f32_e32 v162, v68, v162
	v_mfma_f32_32x32x16_bf16 v[112:127], v[244:247], v[238:241], v[112:127]
	v_exp_f32_e32 v70, v70
	v_exp_f32_e32 v71, v71
	v_add_f32_e32 v162, v69, v162
	s_add_i32 m0, s98, 0x4000
	v_mfma_f32_32x32x16_bf16 v[96:111], v[248:251], v[238:241], v[96:111]
	global_load_lds_dwordx4 v180, s[6:7]
	s_waitcnt lgkmcnt(0)
	ds_read_b128 v[244:247], v190 offset:57600
	ds_read_b128 v[248:251], v191 offset:12544
	ds_read_b128 v[238:241], v215 offset:2048
	v_add_f32_e32 v162, v88, v162
	v_add_f32_e32 v162, v89, v162
	v_add_f32_e32 v162, v70, v162
	v_mfma_f32_32x32x16_bf16 v[112:127], v[230:233], v[136:139], v[112:127]
	v_exp_f32_e32 v72, v72
	v_exp_f32_e32 v73, v73
	v_add_f32_e32 v162, v71, v162
	s_add_i32 m0, s98, 0x6000
	v_mfma_f32_32x32x16_bf16 v[96:111], v[234:237], v[136:139], v[96:111]
	global_load_lds_dwordx4 v181, s[6:7]
	s_waitcnt lgkmcnt(0)
	ds_read_b128 v[230:233], v192 offset:57344
	ds_read_b128 v[234:237], v193 offset:12288
	v_add_f32_e32 v162, v90, v162
	v_add_f32_e32 v162, v91, v162
	v_add_f32_e32 v162, v72, v162
	v_mfma_f32_32x32x16_bf16 v[112:127], v[244:247], v[238:241], v[112:127]
	v_exp_f32_e32 v74, v74
	v_exp_f32_e32 v75, v75
	v_add_f32_e32 v162, v73, v162
	v_mfma_f32_32x32x16_bf16 v[96:111], v[248:251], v[238:241], v[96:111]
	s_waitcnt lgkmcnt(0)
	ds_read_b128 v[244:247], v192 offset:57600
	ds_read_b128 v[248:251], v193 offset:12544
	ds_read_b128 v[238:241], v215 offset:3072
	v_add_f32_e32 v162, v92, v162
	v_add_f32_e32 v162, v93, v162
	v_add_f32_e32 v162, v74, v162
	v_mfma_f32_32x32x16_bf16 v[112:127], v[230:233], v[156:159], v[112:127]
	v_exp_f32_e32 v76, v76
	v_exp_f32_e32 v77, v77
	v_add_f32_e32 v162, v75, v162
	v_mfma_f32_32x32x16_bf16 v[96:111], v[234:237], v[156:159], v[96:111]
	s_waitcnt lgkmcnt(0)
	ds_read_b128 v[230:233], v186 offset:57472
	ds_read_b128 v[234:237], v187 offset:12416
	v_add_f32_e32 v162, v94, v162
	v_add_f32_e32 v162, v95, v162
	v_add_f32_e32 v162, v76, v162
	v_mfma_f32_32x32x16_bf16 v[112:127], v[244:247], v[238:241], v[112:127]
	v_exp_f32_e32 v78, v78
	v_exp_f32_e32 v79, v79
	v_add_f32_e32 v162, v77, v162
	v_mfma_f32_32x32x16_bf16 v[96:111], v[248:251], v[238:241], v[96:111]
	s_waitcnt lgkmcnt(0)
	ds_read_b128 v[244:247], v188 offset:57472
	ds_read_b128 v[248:251], v189 offset:12416
	v_add_f32_e32 v162, v162, v78
	v_cvt_pk_bf16_f32 v80, v80, v81
	v_cvt_pk_bf16_f32 v81, v82, v83
	v_cvt_pk_bf16_f32 v82, v84, v85
	v_mfma_f32_32x32x16_bf16 v[112:127], v[230:233], v[152:155], v[112:127]
	v_cvt_pk_bf16_f32 v83, v86, v87
	v_add_f32_e32 v227, v79, v162
	v_permlane32_swap_b32_e32 v80, v82
	v_permlane32_swap_b32_e32 v81, v83
	v_mfma_f32_32x32x16_bf16 v[96:111], v[234:237], v[152:155], v[96:111]
	s_waitcnt lgkmcnt(0)
	ds_read_b128 v[230:233], v190 offset:57472
	ds_read_b128 v[234:237], v191 offset:12416
	v_cvt_pk_bf16_f32 v84, v88, v89
	v_cvt_pk_bf16_f32 v85, v90, v91
	v_cvt_pk_bf16_f32 v86, v92, v93
	v_mfma_f32_32x32x16_bf16 v[112:127], v[244:247], v[148:151], v[112:127]
	v_cvt_pk_bf16_f32 v87, v94, v95
	v_permlane32_swap_b32_e32 v84, v86
	v_mfma_f32_32x32x16_bf16 v[96:111], v[248:251], v[148:151], v[96:111]
	v_permlane32_swap_b32_e32 v85, v87
	s_waitcnt lgkmcnt(0)
	ds_read_b128 v[244:247], v192 offset:57472
	ds_read_b128 v[248:251], v193 offset:12416
	v_cvt_pk_bf16_f32 v64, v64, v65
	v_cvt_pk_bf16_f32 v65, v66, v67
	v_cvt_pk_bf16_f32 v66, v68, v69
	v_mfma_f32_32x32x16_bf16 v[112:127], v[230:233], v[144:147], v[112:127]
	v_cvt_pk_bf16_f32 v67, v70, v71
	v_permlane32_swap_b32_e32 v64, v66
	v_mfma_f32_32x32x16_bf16 v[96:111], v[234:237], v[144:147], v[96:111]
	v_permlane32_swap_b32_e32 v65, v67
	s_waitcnt lgkmcnt(0)
; #define LAS __attribute__((address_space(3)))
; __device__ __forceinline__ float fma_s(float a, float b, float c) { float d; asm volatile("v_fma_f32 %0, %1, %2, %3" : "=v"(d) : "v"(a), "v"(b), "v"(c)); return d; }
; template <int S> __device__ __forceinline__ void psm_chunk(f32x16& p0, f32x16& p1, float& mx, float& m_reg, float& alpha, float& mnC) {
;   constexpr float C = SCALE * 1.4426950408889634f; const float Cv = C;
;   if constexpr (S == 0) { mx = p0[0];
; #pragma unroll
;     for (int r = 1; r < 16; ++r) mx = fmaxf(mx, p0[r]); }
;   else if constexpr (S == 1) {
; #pragma unroll
;     for (int r = 0; r < 16; ++r) mx = fmaxf(mx, p1[r]);
;     { auto rr = __builtin_amdgcn_permlane32_swap(__float_as_uint(mx), __float_as_uint(mx), false, false); mx = fmaxf(__uint_as_float(rr[0]), __uint_as_float(rr[1])); }
;     const float mn = (mx - m_reg > THR / SCALE) ? fmaxf(m_reg, mx) : m_reg; alpha = __builtin_amdgcn_exp2f((m_reg - mn) * C); m_reg = mn; mnC = -mn * C; }
;   else if constexpr (S == 2) {
; #pragma unroll
;     for (int r = 0; r < 8; ++r) p0[r] = fma_s(p0[r], Cv, mnC); }
;   else if constexpr (S == 3) {
; #pragma unroll
;     for (int r = 8; r < 16; ++r) p0[r] = fma_s(p0[r], Cv, mnC);
; #pragma unroll
;     for (int r = 0; r < 4; ++r) p0[r] = __builtin_amdgcn_exp2f(p0[r]); }
;   else if constexpr (S == 4) {
; #pragma unroll
;     for (int r = 0; r < 8; ++r) p1[r] = fma_s(p1[r], Cv, mnC);
; #pragma unroll
;     for (int r = 4; r < 8; ++r) p0[r] = __builtin_amdgcn_exp2f(p0[r]); }
;   else if constexpr (S == 5) {
; #pragma unroll
;     for (int r = 8; r < 16; ++r) p1[r] = fma_s(p1[r], Cv, mnC);
; #pragma unroll
;     for (int r = 8; r < 12; ++r) p0[r] = __builtin_amdgcn_exp2f(p0[r]); }
;   else if constexpr (S == 6) {
; #pragma unroll
;     for (int r = 12; r < 16; ++r) p0[r] = __builtin_amdgcn_exp2f(p0[r]); }
;   if constexpr (S == 0 || S == 1) asm volatile("" : "+v"(mx), "+v"(alpha), "+v"(mnC), "+v"(m_reg));
;   else if constexpr (S < 7) asm volatile("" : "+v"(p0), "+v"(p1));
; }
; __device__ __forceinline__ void pv_psm(f32x16* o, const LAS char* vl, bf16x8 pa0, bf16x8 pa1, bf16x8 pa2, bf16x8 pa3, f32x16& n0, f32x16& n1, float& m_reg, float& alN) {
;   float mx = 0.f, mnC = 0.f;
;     ...
;   VSLOT(0) VSLOT(1) VSLOT(2) VSLOT(3) VSLOT(4) VSLOT(5) VSLOT(6) VSLOT(7)
	ds_read_b64_tr_b16 v[234:235], v184
	ds_read_b64_tr_b16 v[236:237], v184 offset:2048
	ds_read_b64_tr_b16 v[238:239], v184 offset:4096
	ds_read_b64_tr_b16 v[240:241], v184 offset:6144
	v_cvt_pk_bf16_f32 v68, v72, v73
	v_cvt_pk_bf16_f32 v69, v74, v75
	v_cvt_pk_bf16_f32 v70, v76, v77
	v_mfma_f32_32x32x16_bf16 v[112:127], v[244:247], v[140:143], v[112:127]
	v_cvt_pk_bf16_f32 v71, v78, v79
	v_permlane32_swap_b32_e32 v68, v70
	v_mfma_f32_32x32x16_bf16 v[96:111], v[248:251], v[140:143], v[96:111]
	v_permlane32_swap_b32_e32 v69, v71
	v_mov_b32_e32 v229, v227
	s_nop 1
	v_permlane32_swap_b32_e32 v227, v229
	s_waitcnt lgkmcnt(0)
	ds_read_b64_tr_b16 v[72:73], v184 offset:8192
	ds_read_b64_tr_b16 v[74:75], v184 offset:10240
	ds_read_b64_tr_b16 v[76:77], v184 offset:12288
	ds_read_b64_tr_b16 v[78:79], v184 offset:14336
	v_max_f32_e32 v88, v113, v113
	v_max_f32_e32 v89, v112, v112
	v_mfma_f32_32x32x16_bf16 v[0:15], v[80:83], v[234:237], v[0:15]
	v_max_f32_e32 v88, v89, v88
	v_max3_f32 v88, v88, v114, v115
	v_max3_f32 v88, v88, v116, v117
	v_max3_f32 v252, v88, v118, v119
	v_max3_f32 v252, v252, v120, v121
	v_max3_f32 v252, v252, v122, v123
	v_max3_f32 v252, v252, v124, v125
	v_mfma_f32_32x32x16_bf16 v[0:15], v[84:87], v[238:241], v[0:15]
	v_max3_f32 v88, v252, v126, v127
	s_waitcnt lgkmcnt(0)
	ds_read_b64_tr_b16 v[234:235], v184 offset:512
	ds_read_b64_tr_b16 v[236:237], v184 offset:2560
	ds_read_b64_tr_b16 v[238:239], v184 offset:4608
	ds_read_b64_tr_b16 v[240:241], v184 offset:6656
	v_max3_f32 v88, v88, v96, v97
	v_max3_f32 v88, v88, v98, v99
	v_max3_f32 v88, v88, v100, v101
	v_max3_f32 v88, v88, v102, v103
	v_mfma_f32_32x32x16_bf16 v[0:15], v[64:67], v[72:75], v[0:15]
	v_max3_f32 v88, v88, v104, v105
	v_max3_f32 v88, v88, v106, v107
	v_max3_f32 v88, v88, v108, v109
	v_max3_f32 v88, v88, v110, v111
	v_mov_b32_e32 v89, v88
	s_nop 1
	v_permlane32_swap_b32_e32 v88, v89
	v_max_f32_e32 v89, v89, v89
	v_max_f32_e32 v88, v88, v88
	v_max_f32_e32 v88, v88, v89
	v_mfma_f32_32x32x16_bf16 v[0:15], v[68:71], v[76:79], v[0:15]
	v_sub_f32_e32 v89, v88, v228
	v_cmp_lt_f32_e32 vcc, s29, v89
	v_max_f32_e32 v89, v228, v228
	v_max_f32_e32 v89, v89, v88
	v_cndmask_b32_e32 v230, v228, v89, vcc
	v_sub_f32_e32 v89, v228, v230
	v_mul_f32_e32 v89, 0x3dd53b94, v89
	v_exp_f32_e32 v223, v89
	v_mul_f32_e32 v89, 0xbdd53b94, v230
	s_waitcnt lgkmcnt(0)
	ds_read_b64_tr_b16 v[72:73], v184 offset:8704
	ds_read_b64_tr_b16 v[74:75], v184 offset:10752
	ds_read_b64_tr_b16 v[76:77], v184 offset:12800
	ds_read_b64_tr_b16 v[78:79], v184 offset:14848
	v_fma_f32 v112, v112, v211, v89
	v_fma_f32 v113, v113, v211, v89
	v_mfma_f32_32x32x16_bf16 v[48:63], v[80:83], v[234:237], v[48:63]
	v_fma_f32 v114, v114, v211, v89
	v_fma_f32 v115, v115, v211, v89
	v_fma_f32 v116, v116, v211, v89
	v_fma_f32 v117, v117, v211, v89
	v_fma_f32 v118, v118, v211, v89
	v_fma_f32 v119, v119, v211, v89
	v_mfma_f32_32x32x16_bf16 v[48:63], v[84:87], v[238:241], v[48:63]
	s_waitcnt lgkmcnt(0)
	ds_read_b64_tr_b16 v[234:235], v184 offset:1024
	ds_read_b64_tr_b16 v[236:237], v184 offset:3072
	ds_read_b64_tr_b16 v[238:239], v184 offset:5120
	ds_read_b64_tr_b16 v[240:241], v184 offset:7168
	v_fma_f32 v120, v120, v211, v89
	v_fma_f32 v121, v121, v211, v89
	v_mfma_f32_32x32x16_bf16 v[48:63], v[64:67], v[72:75], v[48:63]
	v_fma_f32 v122, v122, v211, v89
	v_fma_f32 v123, v123, v211, v89
	v_fma_f32 v124, v124, v211, v89
	v_exp_f32_e32 v112, v112
	v_exp_f32_e32 v113, v113
	v_exp_f32_e32 v114, v114
	v_exp_f32_e32 v115, v115
	v_mfma_f32_32x32x16_bf16 v[48:63], v[68:71], v[76:79], v[48:63]
	v_fma_f32 v125, v125, v211, v89
	v_fma_f32 v126, v126, v211, v89
	v_fma_f32 v127, v127, v211, v89
	s_nop 0
	s_waitcnt lgkmcnt(0)
	ds_read_b64_tr_b16 v[72:73], v184 offset:9216
	ds_read_b64_tr_b16 v[74:75], v184 offset:11264
	ds_read_b64_tr_b16 v[76:77], v184 offset:13312
	ds_read_b64_tr_b16 v[78:79], v184 offset:15360
	v_fma_f32 v96, v96, v211, v89
	v_fma_f32 v97, v97, v211, v89
	v_mfma_f32_32x32x16_bf16 v[32:47], v[80:83], v[234:237], v[32:47]
	v_fma_f32 v98, v98, v211, v89
	v_fma_f32 v99, v99, v211, v89
	v_fma_f32 v100, v100, v211, v89
	v_exp_f32_e32 v116, v116
	v_exp_f32_e32 v117, v117
	v_exp_f32_e32 v118, v118
	v_exp_f32_e32 v119, v119
	v_mfma_f32_32x32x16_bf16 v[32:47], v[84:87], v[238:241], v[32:47]
	v_fma_f32 v101, v101, v211, v89
	v_fma_f32 v102, v102, v211, v89
	v_fma_f32 v103, v103, v211, v89
	s_nop 0
	s_waitcnt lgkmcnt(0)
	ds_read_b64_tr_b16 v[234:235], v184 offset:1536
	ds_read_b64_tr_b16 v[236:237], v184 offset:3584
	ds_read_b64_tr_b16 v[238:239], v184 offset:5632
	ds_read_b64_tr_b16 v[240:241], v184 offset:7680
	v_fma_f32 v104, v104, v211, v89
	v_fma_f32 v105, v105, v211, v89
	v_mfma_f32_32x32x16_bf16 v[32:47], v[64:67], v[72:75], v[32:47]
	v_fma_f32 v106, v106, v211, v89
	v_fma_f32 v107, v107, v211, v89
	v_fma_f32 v108, v108, v211, v89
	v_exp_f32_e32 v120, v120
	v_exp_f32_e32 v121, v121
	v_exp_f32_e32 v122, v122
	v_exp_f32_e32 v123, v123
	v_mfma_f32_32x32x16_bf16 v[32:47], v[68:71], v[76:79], v[32:47]
	v_fma_f32 v109, v109, v211, v89
	v_fma_f32 v110, v110, v211, v89
	v_fma_f32 v111, v111, v211, v89
	s_nop 0
	s_waitcnt lgkmcnt(0)
	ds_read_b64_tr_b16 v[72:73], v184 offset:9728
	ds_read_b64_tr_b16 v[74:75], v184 offset:11776
	ds_read_b64_tr_b16 v[76:77], v184 offset:13824
	ds_read_b64_tr_b16 v[78:79], v184 offset:15872
	v_exp_f32_e32 v124, v124
	v_exp_f32_e32 v125, v125
	v_mfma_f32_32x32x16_bf16 v[16:31], v[80:83], v[234:237], v[16:31]
	v_exp_f32_e32 v126, v126
	v_exp_f32_e32 v127, v127
	v_mfma_f32_32x32x16_bf16 v[16:31], v[84:87], v[238:241], v[16:31]
	s_waitcnt lgkmcnt(0)
	v_mfma_f32_32x32x16_bf16 v[16:31], v[64:67], v[72:75], v[16:31]
	v_mfma_f32_32x32x16_bf16 v[16:31], v[68:71], v[76:79], v[16:31]
	s_waitcnt vmcnt(0) lgkmcnt(0)
	s_barrier
; #define LAS __attribute__((address_space(3)))
; template <int S> __device__ __forceinline__ void fsm_chunk(f32x16& c0, f32x16& c1, float& ps, bf16x8& pa0, bf16x8& pa1, bf16x8& pa2, bf16x8& pa3) {
;   if constexpr (S < 8) { c1[2 * S] = __builtin_amdgcn_exp2f(c1[2 * S]); c1[2 * S + 1] = __builtin_amdgcn_exp2f(c1[2 * S + 1]); ps += c0[2 * S]; ps += c0[2 * S + 1]; if constexpr (S > 0) { ps += c1[2 * S - 2]; ps += c1[2 * S - 1]; } asm volatile("" : "+v"(c1), "+v"(ps)); }
;   else if constexpr (S == 8) { ps += c1[14]; ps += c1[15]; PK4(c0, 0, pa0); asm volatile("" : "+v"(pa0), "+v"(ps)); }
;   else if constexpr (S == 9) { PK4(c0, 8, pa1); asm volatile("" : "+v"(pa1)); }
;   else if constexpr (S == 10) { PK4(c1, 0, pa2); asm volatile("" : "+v"(pa2)); }
;   else { PK4(c1, 8, pa3); asm volatile("" : "+v"(pa3)); }
; }
; __device__ __forceinline__ void qk_fsm(f32x16& n0, f32x16& n1, f32x16& c0, f32x16& c1, float alC, float& l_reg, bf16x8& pa0, bf16x8& pa1, bf16x8& pa2, bf16x8& pa3,
;                                        const LAS char* kl, const int (&kx)[4], const bf16x8* qr, const LAS char* qrl) {
;   float ps = 0.f;
;     ...
;   QSLOT(0) QSLOT(1) QSLOT(2) QSLOT(3) QSLOT(4) QSLOT(5) QSLOT(6) QSLOT(7) QSLOT(8) QSLOT(9) QSLOT(10) QSLOT(11)
;     ...
;   { auto rr = __builtin_amdgcn_permlane32_swap(__float_as_uint(ps), __float_as_uint(ps), false, false); ps = __uint_as_float(rr[0]) + __uint_as_float(rr[1]); }
;   l_reg = l_reg * alC + ps;
; }
	v_cmp_gt_f32_e32 vcc, 1.0, v223
	s_cbranch_vccz .LBB0_1015
	s_and_saveexec_b64 s[6:7], s[40:41]
	ds_write_b32 v185, v223 offset:128
	s_or_b64 exec, exec, s[6:7]
	s_waitcnt lgkmcnt(0)
	ds_read_b128 v[64:67], v196 offset:224
	ds_read_b128 v[68:71], v196 offset:192
	ds_read_b128 v[72:75], v196 offset:160
	ds_read_b128 v[76:79], v196 offset:128
	s_waitcnt lgkmcnt(0)
	v_pk_mul_f32 v[12:13], v[12:13], v[64:65]
	v_pk_mul_f32 v[8:9], v[8:9], v[68:69]
	v_pk_mul_f32 v[4:5], v[4:5], v[72:73]
	v_pk_mul_f32 v[14:15], v[14:15], v[66:67]
	v_pk_mul_f32 v[10:11], v[10:11], v[70:71]
	v_pk_mul_f32 v[6:7], v[6:7], v[74:75]
	v_pk_mul_f32 v[2:3], v[2:3], v[78:79]
	v_pk_mul_f32 v[0:1], v[0:1], v[76:77]
	v_pk_mul_f32 v[60:61], v[60:61], v[64:65]
	v_pk_mul_f32 v[56:57], v[56:57], v[68:69]
	v_pk_mul_f32 v[52:53], v[52:53], v[72:73]
	v_pk_mul_f32 v[62:63], v[62:63], v[66:67]
	v_pk_mul_f32 v[58:59], v[58:59], v[70:71]
	v_pk_mul_f32 v[54:55], v[54:55], v[74:75]
	v_pk_mul_f32 v[50:51], v[50:51], v[78:79]
	v_pk_mul_f32 v[48:49], v[48:49], v[76:77]
	v_pk_mul_f32 v[44:45], v[44:45], v[64:65]
	v_pk_mul_f32 v[40:41], v[40:41], v[68:69]
	v_pk_mul_f32 v[36:37], v[36:37], v[72:73]
	v_pk_mul_f32 v[46:47], v[46:47], v[66:67]
	v_pk_mul_f32 v[42:43], v[42:43], v[70:71]
	v_pk_mul_f32 v[38:39], v[38:39], v[74:75]
	v_pk_mul_f32 v[34:35], v[34:35], v[78:79]
	v_pk_mul_f32 v[32:33], v[32:33], v[76:77]
	v_pk_mul_f32 v[28:29], v[28:29], v[64:65]
	v_pk_mul_f32 v[24:25], v[24:25], v[68:69]
	v_pk_mul_f32 v[20:21], v[20:21], v[72:73]
	v_pk_mul_f32 v[30:31], v[30:31], v[66:67]
	v_pk_mul_f32 v[26:27], v[26:27], v[70:71]
	v_pk_mul_f32 v[22:23], v[22:23], v[74:75]
	v_pk_mul_f32 v[18:19], v[18:19], v[78:79]
	v_pk_mul_f32 v[16:17], v[16:17], v[76:77]
.LBB0_1015:
	ds_read_b128 v[232:235], v186 offset:32768
	ds_read_b128 v[236:239], v186 offset:45056
	s_add_u32 s4, s12, s31
	s_addc_u32 s5, s13, s9
	s_add_u32 s4, s4, 0x1dd12000
	s_addc_u32 s5, s5, 0
	s_add_u32 s6, s12, s90
	s_addc_u32 s7, s13, s91
	s_add_u32 s6, s6, 0x25508000
	s_addc_u32 s7, s7, 0
	s_waitcnt lgkmcnt(0)
	ds_read_b128 v[244:247], v186 offset:33024
	ds_read_b128 v[248:251], v186 offset:45312
	ds_read_b128 v[240:243], v215
	v_exp_f32_e32 v96, v96
	v_exp_f32_e32 v97, v97
	v_mfma_f32_32x32x16_bf16 v[80:95], v[232:235], v[128:131], 0
	v_add_f32_e32 v64, 0, v112
	v_add_f32_e32 v162, v113, v64
	s_add_i32 m0, s98, 0xe000
	v_mfma_f32_32x32x16_bf16 v[64:79], v[236:239], v[128:131], 0
	global_load_lds_dwordx4 v177, s[4:5]
	s_waitcnt lgkmcnt(0)
	ds_read_b128 v[232:235], v188 offset:32768
	ds_read_b128 v[236:239], v188 offset:45056
	v_add_f32_e32 v162, v114, v162
	v_add_f32_e32 v162, v115, v162
	v_add_f32_e32 v162, v96, v162
	v_mfma_f32_32x32x16_bf16 v[80:95], v[244:247], v[240:243], v[80:95]
	v_exp_f32_e32 v98, v98
	v_exp_f32_e32 v99, v99
	v_add_f32_e32 v162, v97, v162
	s_add_i32 m0, s98, 0x10000
	v_mfma_f32_32x32x16_bf16 v[64:79], v[248:251], v[240:243], v[64:79]
	global_load_lds_dwordx4 v178, s[4:5]
	s_waitcnt lgkmcnt(0)
	ds_read_b128 v[244:247], v188 offset:33024
	ds_read_b128 v[248:251], v188 offset:45312
	ds_read_b128 v[240:243], v215 offset:1024
	v_add_f32_e32 v162, v116, v162
	v_add_f32_e32 v162, v117, v162
	v_add_f32_e32 v162, v98, v162
	v_mfma_f32_32x32x16_bf16 v[80:95], v[232:235], v[132:135], v[80:95]
	v_exp_f32_e32 v100, v100
	v_exp_f32_e32 v101, v101
	v_add_f32_e32 v162, v99, v162
	s_add_i32 m0, s98, 0x12000
	v_mfma_f32_32x32x16_bf16 v[64:79], v[236:239], v[132:135], v[64:79]
	global_load_lds_dwordx4 v179, s[4:5]
	s_waitcnt lgkmcnt(0)
	ds_read_b128 v[232:235], v190 offset:32768
	ds_read_b128 v[236:239], v190 offset:45056
	v_add_f32_e32 v162, v118, v162
	v_add_f32_e32 v162, v119, v162
	v_add_f32_e32 v162, v100, v162
	v_mfma_f32_32x32x16_bf16 v[80:95], v[244:247], v[240:243], v[80:95]
	v_exp_f32_e32 v102, v102
	v_exp_f32_e32 v103, v103
	v_add_f32_e32 v162, v101, v162
	s_mov_b32 m0, s98
	v_mfma_f32_32x32x16_bf16 v[64:79], v[248:251], v[240:243], v[64:79]
	global_load_lds_dwordx4 v180, s[6:7]
	s_waitcnt lgkmcnt(0)
	ds_read_b128 v[244:247], v190 offset:33024
	ds_read_b128 v[248:251], v190 offset:45312
	ds_read_b128 v[240:243], v215 offset:2048
	v_add_f32_e32 v162, v120, v162
	v_add_f32_e32 v162, v121, v162
	v_add_f32_e32 v162, v102, v162
	v_mfma_f32_32x32x16_bf16 v[80:95], v[232:235], v[136:139], v[80:95]
	v_exp_f32_e32 v104, v104
	v_exp_f32_e32 v105, v105
	v_add_f32_e32 v162, v103, v162
	s_add_i32 m0, s98, 0x2000
	v_mfma_f32_32x32x16_bf16 v[64:79], v[236:239], v[136:139], v[64:79]
	global_load_lds_dwordx4 v181, s[6:7]
	s_waitcnt lgkmcnt(0)
	ds_read_b128 v[232:235], v192 offset:32768
	ds_read_b128 v[236:239], v192 offset:45056
	v_add_f32_e32 v162, v122, v162
	v_add_f32_e32 v162, v123, v162
	v_add_f32_e32 v162, v104, v162
	v_mfma_f32_32x32x16_bf16 v[80:95], v[244:247], v[240:243], v[80:95]
	v_exp_f32_e32 v106, v106
	v_exp_f32_e32 v107, v107
	v_add_f32_e32 v162, v105, v162
	v_mfma_f32_32x32x16_bf16 v[64:79], v[248:251], v[240:243], v[64:79]
	s_waitcnt lgkmcnt(0)
	ds_read_b128 v[244:247], v192 offset:33024
	ds_read_b128 v[248:251], v192 offset:45312
	ds_read_b128 v[240:243], v215 offset:3072
	v_add_f32_e32 v162, v124, v162
	v_add_f32_e32 v162, v125, v162
	v_add_f32_e32 v162, v106, v162
	v_mfma_f32_32x32x16_bf16 v[80:95], v[232:235], v[156:159], v[80:95]
	v_exp_f32_e32 v108, v108
	v_exp_f32_e32 v109, v109
	v_add_f32_e32 v162, v107, v162
	v_mfma_f32_32x32x16_bf16 v[64:79], v[236:239], v[156:159], v[64:79]
	s_waitcnt lgkmcnt(0)
	ds_read_b128 v[232:235], v186 offset:32896
	ds_read_b128 v[236:239], v186 offset:45184
	v_add_f32_e32 v162, v126, v162
	v_add_f32_e32 v162, v127, v162
	v_add_f32_e32 v162, v108, v162
	v_mfma_f32_32x32x16_bf16 v[80:95], v[244:247], v[240:243], v[80:95]
	v_exp_f32_e32 v110, v110
	v_exp_f32_e32 v111, v111
	v_add_f32_e32 v162, v109, v162
	v_mfma_f32_32x32x16_bf16 v[64:79], v[248:251], v[240:243], v[64:79]
	s_waitcnt lgkmcnt(0)
; template <int S> __device__ __forceinline__ void fsm_chunk(f32x16& c0, f32x16& c1, float& ps, bf16x8& pa0, bf16x8& pa1, bf16x8& pa2, bf16x8& pa3) {
;   if constexpr (S < 8) { c1[2 * S] = __builtin_amdgcn_exp2f(c1[2 * S]); c1[2 * S + 1] = __builtin_amdgcn_exp2f(c1[2 * S + 1]); ps += c0[2 * S]; ps += c0[2 * S + 1]; if constexpr (S > 0) { ps += c1[2 * S - 2]; ps += c1[2 * S - 1]; } asm volatile("" : "+v"(c1), "+v"(ps)); }
;   else if constexpr (S == 8) { ps += c1[14]; ps += c1[15]; PK4(c0, 0, pa0); asm volatile("" : "+v"(pa0), "+v"(ps)); }
;   else if constexpr (S == 9) { PK4(c0, 8, pa1); asm volatile("" : "+v"(pa1)); }
;   else if constexpr (S == 10) { PK4(c1, 0, pa2); asm volatile("" : "+v"(pa2)); }
;   else { PK4(c1, 8, pa3); asm volatile("" : "+v"(pa3)); }
; }
; __device__ __forceinline__ void qk_fsm(f32x16& n0, f32x16& n1, f32x16& c0, f32x16& c1, float alC, float& l_reg, bf16x8& pa0, bf16x8& pa1, bf16x8& pa2, bf16x8& pa3,
;                                        const LAS char* kl, const int (&kx)[4], const bf16x8* qr, const LAS char* qrl) {
;   float ps = 0.f;
;     ...
;   QSLOT(0) QSLOT(1) QSLOT(2) QSLOT(3) QSLOT(4) QSLOT(5) QSLOT(6) QSLOT(7) QSLOT(8) QSLOT(9) QSLOT(10) QSLOT(11)
;     ...
;   { auto rr = __builtin_amdgcn_permlane32_swap(__float_as_uint(ps), __float_as_uint(ps), false, false); ps = __uint_as_float(rr[0]) + __uint_as_float(rr[1]); }
;   l_reg = l_reg * alC + ps;
; template <int S> __device__ __forceinline__ void psm_chunk(f32x16& p0, f32x16& p1, float& mx, float& m_reg, float& alpha, float& mnC) {
;   constexpr float C = SCALE * 1.4426950408889634f; const float Cv = C;
;   if constexpr (S == 0) { mx = p0[0];
; #pragma unroll
;     for (int r = 1; r < 16; ++r) mx = fmaxf(mx, p0[r]); }
;   else if constexpr (S == 1) {
; #pragma unroll
;     for (int r = 0; r < 16; ++r) mx = fmaxf(mx, p1[r]);
;     { auto rr = __builtin_amdgcn_permlane32_swap(__float_as_uint(mx), __float_as_uint(mx), false, false); mx = fmaxf(__uint_as_float(rr[0]), __uint_as_float(rr[1])); }
;     const float mn = (mx - m_reg > THR / SCALE) ? fmaxf(m_reg, mx) : m_reg; alpha = __builtin_amdgcn_exp2f((m_reg - mn) * C); m_reg = mn; mnC = -mn * C; }
;   else if constexpr (S == 2) {
; #pragma unroll
;     for (int r = 0; r < 8; ++r) p0[r] = fma_s(p0[r], Cv, mnC); }
;   else if constexpr (S == 3) {
; #pragma unroll
;     for (int r = 8; r < 16; ++r) p0[r] = fma_s(p0[r], Cv, mnC);
	ds_read_b128 v[244:247], v188 offset:32896
	ds_read_b128 v[248:251], v188 offset:45184
	v_add_f32_e32 v162, v162, v110
	v_cvt_pk_bf16_f32 v112, v112, v113
	v_cvt_pk_bf16_f32 v113, v114, v115
	v_cvt_pk_bf16_f32 v114, v116, v117
	v_mfma_f32_32x32x16_bf16 v[80:95], v[232:235], v[152:155], v[80:95]
	v_cvt_pk_bf16_f32 v115, v118, v119
	v_add_f32_e32 v231, v111, v162
	v_permlane32_swap_b32_e32 v112, v114
	v_permlane32_swap_b32_e32 v113, v115
	v_mfma_f32_32x32x16_bf16 v[64:79], v[236:239], v[152:155], v[64:79]
	s_waitcnt lgkmcnt(0)
	ds_read_b128 v[232:235], v190 offset:32896
	ds_read_b128 v[236:239], v190 offset:45184
	v_cvt_pk_bf16_f32 v116, v120, v121
	v_cvt_pk_bf16_f32 v117, v122, v123
	v_cvt_pk_bf16_f32 v118, v124, v125
	v_mfma_f32_32x32x16_bf16 v[80:95], v[244:247], v[148:151], v[80:95]
	v_cvt_pk_bf16_f32 v119, v126, v127
	v_permlane32_swap_b32_e32 v116, v118
	v_mfma_f32_32x32x16_bf16 v[64:79], v[248:251], v[148:151], v[64:79]
	v_permlane32_swap_b32_e32 v117, v119
	s_waitcnt lgkmcnt(0)
	ds_read_b128 v[244:247], v192 offset:32896
	ds_read_b128 v[248:251], v192 offset:45184
	v_cvt_pk_bf16_f32 v96, v96, v97
	v_cvt_pk_bf16_f32 v97, v98, v99
	v_cvt_pk_bf16_f32 v98, v100, v101
	v_mfma_f32_32x32x16_bf16 v[80:95], v[232:235], v[144:147], v[80:95]
	v_cvt_pk_bf16_f32 v99, v102, v103
	v_permlane32_swap_b32_e32 v96, v98
	v_mfma_f32_32x32x16_bf16 v[64:79], v[236:239], v[144:147], v[64:79]
	v_permlane32_swap_b32_e32 v97, v99
	s_waitcnt lgkmcnt(0)
	ds_read_b64_tr_b16 v[232:233], v184 offset:16384
	ds_read_b64_tr_b16 v[234:235], v184 offset:18432
	ds_read_b64_tr_b16 v[236:237], v184 offset:20480
	ds_read_b64_tr_b16 v[238:239], v184 offset:22528
	v_cvt_pk_bf16_f32 v100, v104, v105
	v_cvt_pk_bf16_f32 v101, v106, v107
	v_cvt_pk_bf16_f32 v102, v108, v109
	v_mfma_f32_32x32x16_bf16 v[80:95], v[244:247], v[140:143], v[80:95]
	v_cvt_pk_bf16_f32 v103, v110, v111
	v_permlane32_swap_b32_e32 v100, v102
	v_mfma_f32_32x32x16_bf16 v[64:79], v[248:251], v[140:143], v[64:79]
	v_permlane32_swap_b32_e32 v101, v103
	v_mov_b32_e32 v104, v231
	s_nop 1
	v_permlane32_swap_b32_e32 v231, v104
	s_waitcnt lgkmcnt(0)
	ds_read_b64_tr_b16 v[106:107], v184 offset:24576
	ds_read_b64_tr_b16 v[108:109], v184 offset:26624
	ds_read_b64_tr_b16 v[120:121], v184 offset:28672
	ds_read_b64_tr_b16 v[122:123], v184 offset:30720
	v_max_f32_e32 v105, v81, v81
	v_max_f32_e32 v110, v80, v80
	v_mfma_f32_32x32x16_bf16 v[0:15], v[112:115], v[232:235], v[0:15]
	v_max_f32_e32 v105, v110, v105
	v_max3_f32 v105, v105, v82, v83
	v_max3_f32 v105, v105, v84, v85
	v_max3_f32 v105, v105, v86, v87
	v_max3_f32 v105, v105, v88, v89
	v_max3_f32 v105, v105, v90, v91
	v_max3_f32 v105, v105, v92, v93
	v_mfma_f32_32x32x16_bf16 v[0:15], v[116:119], v[236:239], v[0:15]
	v_max3_f32 v105, v105, v94, v95
	s_waitcnt lgkmcnt(0)
	ds_read_b64_tr_b16 v[232:233], v184 offset:16896
	ds_read_b64_tr_b16 v[234:235], v184 offset:18944
	ds_read_b64_tr_b16 v[236:237], v184 offset:20992
	ds_read_b64_tr_b16 v[238:239], v184 offset:23040
	v_max3_f32 v105, v105, v64, v65
	v_max3_f32 v105, v105, v66, v67
	v_max3_f32 v105, v105, v68, v69
	v_max3_f32 v105, v105, v70, v71
	v_mfma_f32_32x32x16_bf16 v[0:15], v[96:99], v[106:109], v[0:15]
	v_max3_f32 v105, v105, v72, v73
	v_max3_f32 v105, v105, v74, v75
	v_max3_f32 v105, v105, v76, v77
	v_max3_f32 v105, v105, v78, v79
	v_mov_b32_e32 v110, v105
	s_nop 1
	v_permlane32_swap_b32_e32 v105, v110
	v_max_f32_e32 v110, v110, v110
	v_max_f32_e32 v105, v105, v105
	v_max_f32_e32 v105, v105, v110
	v_mfma_f32_32x32x16_bf16 v[0:15], v[100:103], v[120:123], v[0:15]
	v_sub_f32_e32 v110, v105, v230
	v_cmp_lt_f32_e32 vcc, s29, v110
	v_max_f32_e32 v110, v230, v230
	v_max_f32_e32 v110, v110, v105
	v_cndmask_b32_e32 v228, v230, v110, vcc
	v_sub_f32_e32 v110, v230, v228
	v_mul_f32_e32 v110, 0x3dd53b94, v110
	v_exp_f32_e32 v162, v110
	v_mul_f32_e32 v110, 0xbdd53b94, v228
	s_waitcnt lgkmcnt(0)
	ds_read_b64_tr_b16 v[106:107], v184 offset:25088
	ds_read_b64_tr_b16 v[108:109], v184 offset:27136
	ds_read_b64_tr_b16 v[120:121], v184 offset:29184
	ds_read_b64_tr_b16 v[122:123], v184 offset:31232
	v_fma_f32 v80, v80, v211, v110
	v_fma_f32 v81, v81, v211, v110
	v_mfma_f32_32x32x16_bf16 v[48:63], v[112:115], v[232:235], v[48:63]
	v_fma_f32 v82, v82, v211, v110
	v_fma_f32 v83, v83, v211, v110
	v_fma_f32 v84, v84, v211, v110
	v_fma_f32 v85, v85, v211, v110
	v_fma_f32 v86, v86, v211, v110
	v_fma_f32 v87, v87, v211, v110
	v_mfma_f32_32x32x16_bf16 v[48:63], v[116:119], v[236:239], v[48:63]
	s_waitcnt lgkmcnt(0)
; #define LAS __attribute__((address_space(3)))
; __device__ __forceinline__ float fma_s(float a, float b, float c) { float d; asm volatile("v_fma_f32 %0, %1, %2, %3" : "=v"(d) : "v"(a), "v"(b), "v"(c)); return d; }
; template <int S> __device__ __forceinline__ void psm_chunk(f32x16& p0, f32x16& p1, float& mx, float& m_reg, float& alpha, float& mnC) {
;   constexpr float C = SCALE * 1.4426950408889634f; const float Cv = C;
;   if constexpr (S == 0) { mx = p0[0];
; #pragma unroll
;     for (int r = 1; r < 16; ++r) mx = fmaxf(mx, p0[r]); }
;   else if constexpr (S == 1) {
; #pragma unroll
;     for (int r = 0; r < 16; ++r) mx = fmaxf(mx, p1[r]);
;     { auto rr = __builtin_amdgcn_permlane32_swap(__float_as_uint(mx), __float_as_uint(mx), false, false); mx = fmaxf(__uint_as_float(rr[0]), __uint_as_float(rr[1])); }
;     const float mn = (mx - m_reg > THR / SCALE) ? fmaxf(m_reg, mx) : m_reg; alpha = __builtin_amdgcn_exp2f((m_reg - mn) * C); m_reg = mn; mnC = -mn * C; }
;   else if constexpr (S == 2) {
; #pragma unroll
;     for (int r = 0; r < 8; ++r) p0[r] = fma_s(p0[r], Cv, mnC); }
;   else if constexpr (S == 3) {
; #pragma unroll
;     for (int r = 8; r < 16; ++r) p0[r] = fma_s(p0[r], Cv, mnC);
; #pragma unroll
;     for (int r = 0; r < 4; ++r) p0[r] = __builtin_amdgcn_exp2f(p0[r]); }
;   else if constexpr (S == 4) {
; #pragma unroll
;     for (int r = 0; r < 8; ++r) p1[r] = fma_s(p1[r], Cv, mnC);
; #pragma unroll
;     for (int r = 4; r < 8; ++r) p0[r] = __builtin_amdgcn_exp2f(p0[r]); }
;   else if constexpr (S == 5) {
; #pragma unroll
;     for (int r = 8; r < 16; ++r) p1[r] = fma_s(p1[r], Cv, mnC);
; #pragma unroll
;     for (int r = 8; r < 12; ++r) p0[r] = __builtin_amdgcn_exp2f(p0[r]); }
;   else if constexpr (S == 6) {
; #pragma unroll
;     for (int r = 12; r < 16; ++r) p0[r] = __builtin_amdgcn_exp2f(p0[r]); }
;   if constexpr (S == 0 || S == 1) asm volatile("" : "+v"(mx), "+v"(alpha), "+v"(mnC), "+v"(m_reg));
;   else if constexpr (S < 7) asm volatile("" : "+v"(p0), "+v"(p1));
; }
; __device__ __forceinline__ void pv_psm(f32x16* o, const LAS char* vl, bf16x8 pa0, bf16x8 pa1, bf16x8 pa2, bf16x8 pa3, f32x16& n0, f32x16& n1, float& m_reg, float& alN) {
;   float mx = 0.f, mnC = 0.f;
;     ...
;   VSLOT(0) VSLOT(1) VSLOT(2) VSLOT(3) VSLOT(4) VSLOT(5) VSLOT(6) VSLOT(7)
;     ...
; }
	ds_read_b64_tr_b16 v[232:233], v184 offset:17408
	ds_read_b64_tr_b16 v[234:235], v184 offset:19456
	ds_read_b64_tr_b16 v[236:237], v184 offset:21504
	ds_read_b64_tr_b16 v[238:239], v184 offset:23552
	v_fma_f32 v88, v88, v211, v110
	v_fma_f32 v89, v89, v211, v110
	v_mfma_f32_32x32x16_bf16 v[48:63], v[96:99], v[106:109], v[48:63]
	v_fma_f32 v90, v90, v211, v110
	v_fma_f32 v91, v91, v211, v110
	v_fma_f32 v92, v92, v211, v110
	v_exp_f32_e32 v80, v80
	v_exp_f32_e32 v81, v81
	v_exp_f32_e32 v82, v82
	v_exp_f32_e32 v83, v83
	v_mfma_f32_32x32x16_bf16 v[48:63], v[100:103], v[120:123], v[48:63]
	v_fma_f32 v93, v93, v211, v110
	v_fma_f32 v94, v94, v211, v110
	v_fma_f32 v95, v95, v211, v110
	s_nop 0
	s_waitcnt lgkmcnt(0)
	ds_read_b64_tr_b16 v[106:107], v184 offset:25600
	ds_read_b64_tr_b16 v[108:109], v184 offset:27648
	ds_read_b64_tr_b16 v[120:121], v184 offset:29696
	ds_read_b64_tr_b16 v[122:123], v184 offset:31744
	v_fma_f32 v64, v64, v211, v110
	v_fma_f32 v65, v65, v211, v110
	v_mfma_f32_32x32x16_bf16 v[32:47], v[112:115], v[232:235], v[32:47]
	v_fma_f32 v66, v66, v211, v110
	v_fma_f32 v67, v67, v211, v110
	v_fma_f32 v68, v68, v211, v110
	v_exp_f32_e32 v84, v84
	v_exp_f32_e32 v85, v85
	v_exp_f32_e32 v86, v86
	v_exp_f32_e32 v87, v87
	v_mfma_f32_32x32x16_bf16 v[32:47], v[116:119], v[236:239], v[32:47]
	v_fma_f32 v69, v69, v211, v110
	v_fma_f32 v70, v70, v211, v110
	v_fma_f32 v71, v71, v211, v110
	s_nop 0
	s_waitcnt lgkmcnt(0)
	ds_read_b64_tr_b16 v[232:233], v184 offset:17920
	ds_read_b64_tr_b16 v[234:235], v184 offset:19968
	ds_read_b64_tr_b16 v[236:237], v184 offset:22016
	ds_read_b64_tr_b16 v[238:239], v184 offset:24064
	v_fma_f32 v72, v72, v211, v110
	v_fma_f32 v73, v73, v211, v110
	v_mfma_f32_32x32x16_bf16 v[32:47], v[96:99], v[106:109], v[32:47]
	v_fma_f32 v74, v74, v211, v110
	v_fma_f32 v75, v75, v211, v110
	v_fma_f32 v76, v76, v211, v110
	v_exp_f32_e32 v88, v88
	v_exp_f32_e32 v89, v89
	v_exp_f32_e32 v90, v90
	v_exp_f32_e32 v91, v91
	v_mfma_f32_32x32x16_bf16 v[32:47], v[100:103], v[120:123], v[32:47]
	v_fma_f32 v77, v77, v211, v110
	v_fma_f32 v78, v78, v211, v110
	v_fma_f32 v79, v79, v211, v110
	s_nop 0
	s_waitcnt lgkmcnt(0)
	ds_read_b64_tr_b16 v[106:107], v184 offset:26112
	ds_read_b64_tr_b16 v[108:109], v184 offset:28160
	ds_read_b64_tr_b16 v[120:121], v184 offset:30208
	ds_read_b64_tr_b16 v[122:123], v184 offset:32256
	v_exp_f32_e32 v92, v92
	v_exp_f32_e32 v93, v93
	v_mfma_f32_32x32x16_bf16 v[16:31], v[112:115], v[232:235], v[16:31]
	v_exp_f32_e32 v94, v94
	v_exp_f32_e32 v95, v95
	v_mfma_f32_32x32x16_bf16 v[16:31], v[116:119], v[236:239], v[16:31]
	s_waitcnt lgkmcnt(0)
	v_mfma_f32_32x32x16_bf16 v[16:31], v[96:99], v[106:109], v[16:31]
	v_mfma_f32_32x32x16_bf16 v[16:31], v[100:103], v[120:123], v[16:31]
	s_waitcnt vmcnt(0) lgkmcnt(0)
	s_barrier
	v_cmp_gt_f32_e32 vcc, 1.0, v162
	s_cbranch_vccz .LBB0_1019
	s_and_saveexec_b64 s[6:7], s[40:41]
	ds_write_b32 v185, v162 offset:128
	s_or_b64 exec, exec, s[6:7]
	s_waitcnt lgkmcnt(0)
	ds_read_b128 v[96:99], v196 offset:224
	ds_read_b128 v[100:103], v196 offset:192
	ds_read_b128 v[106:109], v196 offset:160
	ds_read_b128 v[110:113], v196 offset:128
	s_waitcnt lgkmcnt(0)
	v_pk_mul_f32 v[12:13], v[12:13], v[96:97]
	v_pk_mul_f32 v[8:9], v[8:9], v[100:101]
	v_pk_mul_f32 v[4:5], v[4:5], v[106:107]
	v_pk_mul_f32 v[14:15], v[14:15], v[98:99]
	v_pk_mul_f32 v[10:11], v[10:11], v[102:103]
	v_pk_mul_f32 v[6:7], v[6:7], v[108:109]
	v_pk_mul_f32 v[2:3], v[2:3], v[112:113]
	v_pk_mul_f32 v[0:1], v[0:1], v[110:111]
	v_pk_mul_f32 v[60:61], v[60:61], v[96:97]
	v_pk_mul_f32 v[56:57], v[56:57], v[100:101]
	v_pk_mul_f32 v[52:53], v[52:53], v[106:107]
	v_pk_mul_f32 v[62:63], v[62:63], v[98:99]
	v_pk_mul_f32 v[58:59], v[58:59], v[102:103]
	v_pk_mul_f32 v[54:55], v[54:55], v[108:109]
	v_pk_mul_f32 v[50:51], v[50:51], v[112:113]
	v_pk_mul_f32 v[48:49], v[48:49], v[110:111]
	v_pk_mul_f32 v[44:45], v[44:45], v[96:97]
	v_pk_mul_f32 v[40:41], v[40:41], v[100:101]
	v_pk_mul_f32 v[36:37], v[36:37], v[106:107]
	v_pk_mul_f32 v[46:47], v[46:47], v[98:99]
	v_pk_mul_f32 v[42:43], v[42:43], v[102:103]
	v_pk_mul_f32 v[38:39], v[38:39], v[108:109]
	v_pk_mul_f32 v[34:35], v[34:35], v[112:113]
	v_pk_mul_f32 v[32:33], v[32:33], v[110:111]
	v_pk_mul_f32 v[28:29], v[28:29], v[96:97]
	v_pk_mul_f32 v[24:25], v[24:25], v[100:101]
	v_pk_mul_f32 v[20:21], v[20:21], v[106:107]
	v_pk_mul_f32 v[30:31], v[30:31], v[98:99]
	v_pk_mul_f32 v[26:27], v[26:27], v[102:103]
	v_pk_mul_f32 v[22:23], v[22:23], v[108:109]
	v_pk_mul_f32 v[18:19], v[18:19], v[112:113]
	v_pk_mul_f32 v[16:17], v[16:17], v[110:111]
